# GEMM K-loops: LDS-DMA issue rebalanced 4+4 between the two load segments (As[b][0] stage moved from SP2 to the following SP1, waits vmcnt 8/6)
# speedup vs baseline: 1.0168x; 1.0053x over previous
.LBB0_367:
	s_add_u32 s6, s4, 0xfff00080
	s_addc_u32 s7, s5, -1
	s_add_i32 s53, 0, 0x10000
	s_cmp_eq_u32 s79, 60
	s_cselect_b32 s31, s27, s7
	s_cselect_b32 s30, s26, s6
	s_cselect_b32 s7, s29, s78
	s_cselect_b32 s6, s28, s55
	s_add_i32 s90, 0, 0x14000
	v_add_u32_e32 v154, s53, v144
	v_add_u32_e32 v170, s90, v144
	ds_read_b128 v[140:143], v154
	ds_read_b128 v[146:149], v154 offset:1024
	ds_read_b128 v[150:153], v154 offset:2048
	ds_read_b128 v[154:157], v154 offset:3072
	ds_read_b128 v[158:161], v170
	ds_read_b128 v[162:165], v170 offset:1024
	ds_read_b128 v[166:169], v170 offset:2048
	ds_read_b128 v[170:173], v170 offset:3072
	s_add_u32 s96, s4, 0xfff00000
	s_addc_u32 s97, s5, -1
	s_mov_b32 m0, s51
	s_nop 0
	global_load_lds_dwordx4 v128, s[96:97]
	s_mov_b32 m0, s52
	s_nop 0
	global_load_lds_dwordx4 v132, s[96:97]
	s_add_i32 m0, s49, 0xc000
	ds_read_b128 v[188:191], v145
	ds_read_b128 v[192:195], v145 offset:1024
	ds_read_b128 v[196:199], v145 offset:2048
	ds_read_b128 v[200:203], v145 offset:3072
	ds_read_b128 v[204:207], v145 offset:4096
	ds_read_b128 v[208:211], v145 offset:5120
	ds_read_b128 v[212:215], v145 offset:6144
	ds_read_b128 v[216:219], v145 offset:7168
	global_load_lds_dwordx4 v136, s[4:5]
	s_add_i32 m0, s49, 0xe000
	s_nop 0
	global_load_lds_dwordx4 v138, s[4:5]
	s_waitcnt vmcnt(8)
	s_waitcnt lgkmcnt(0)
	s_barrier
	s_setprio 1
	s_waitcnt lgkmcnt(0)
	v_mfma_f32_16x16x32_bf16 v[124:127], v[140:143], v[188:191], v[124:127]
	v_mfma_f32_16x16x32_bf16 v[120:123], v[150:153], v[188:191], v[120:123]
	v_mfma_f32_16x16x32_bf16 v[108:111], v[140:143], v[196:199], v[108:111]
	v_mfma_f32_16x16x32_bf16 v[104:107], v[150:153], v[196:199], v[104:107]
	v_mfma_f32_16x16x32_bf16 v[92:95], v[140:143], v[204:207], v[92:95]
	v_mfma_f32_16x16x32_bf16 v[88:91], v[150:153], v[204:207], v[88:91]
	v_mfma_f32_16x16x32_bf16 v[76:79], v[140:143], v[212:215], v[76:79]
	v_mfma_f32_16x16x32_bf16 v[72:75], v[150:153], v[212:215], v[72:75]
	v_mfma_f32_16x16x32_bf16 v[124:127], v[146:149], v[192:195], v[124:127]
	v_mfma_f32_16x16x32_bf16 v[120:123], v[154:157], v[192:195], v[120:123]
	v_mfma_f32_16x16x32_bf16 v[108:111], v[146:149], v[200:203], v[108:111]
	v_mfma_f32_16x16x32_bf16 v[104:107], v[154:157], v[200:203], v[104:107]
	v_mfma_f32_16x16x32_bf16 v[92:95], v[146:149], v[208:211], v[92:95]
	v_mfma_f32_16x16x32_bf16 v[88:91], v[154:157], v[208:211], v[88:91]
	v_mfma_f32_16x16x32_bf16 v[76:79], v[146:149], v[216:219], v[76:79]
	v_mfma_f32_16x16x32_bf16 v[72:75], v[154:157], v[216:219], v[72:75]
	s_setprio 0
	s_setprio 1
	v_mfma_f32_16x16x32_bf16 v[116:119], v[158:161], v[188:191], v[116:119]
	v_mfma_f32_16x16x32_bf16 v[112:115], v[166:169], v[188:191], v[112:115]
	v_mfma_f32_16x16x32_bf16 v[100:103], v[158:161], v[196:199], v[100:103]
	v_mfma_f32_16x16x32_bf16 v[96:99], v[166:169], v[196:199], v[96:99]
	v_mfma_f32_16x16x32_bf16 v[84:87], v[158:161], v[204:207], v[84:87]
	v_mfma_f32_16x16x32_bf16 v[80:83], v[166:169], v[204:207], v[80:83]
	v_mfma_f32_16x16x32_bf16 v[68:71], v[158:161], v[212:215], v[68:71]
	v_mfma_f32_16x16x32_bf16 v[64:67], v[166:169], v[212:215], v[64:67]
	v_mfma_f32_16x16x32_bf16 v[116:119], v[162:165], v[192:195], v[116:119]
	v_mfma_f32_16x16x32_bf16 v[112:115], v[170:173], v[192:195], v[112:115]
	v_mfma_f32_16x16x32_bf16 v[100:103], v[162:165], v[200:203], v[100:103]
	v_mfma_f32_16x16x32_bf16 v[96:99], v[170:173], v[200:203], v[96:99]
	v_mfma_f32_16x16x32_bf16 v[84:87], v[162:165], v[208:211], v[84:87]
	v_mfma_f32_16x16x32_bf16 v[80:83], v[170:173], v[208:211], v[80:83]
	v_mfma_f32_16x16x32_bf16 v[68:71], v[162:165], v[216:219], v[68:71]
	v_mfma_f32_16x16x32_bf16 v[64:67], v[170:173], v[216:219], v[64:67]
	s_setprio 0
	s_barrier
	s_add_i32 s53, s53, s43
	s_add_u32 s38, s6, 0x80
	s_addc_u32 s39, s7, 0
	s_mov_b32 m0, s53
	ds_read_b128 v[188:191], v145 offset:16384
	ds_read_b128 v[192:195], v145 offset:17408
	ds_read_b128 v[196:199], v145 offset:18432
	ds_read_b128 v[200:203], v145 offset:19456
	ds_read_b128 v[204:207], v145 offset:20480
	ds_read_b128 v[208:211], v145 offset:21504
	ds_read_b128 v[212:215], v145 offset:22528
	ds_read_b128 v[216:219], v145 offset:23552
	global_load_lds_dwordx4 v130, s[6:7]
	s_add_i32 m0, s53, 0x2000
	s_add_u32 s80, s6, 0x100000
	s_addc_u32 s81, s7, 0
	s_add_i32 s53, s90, s43
	global_load_lds_dwordx4 v134, s[6:7]
	s_mov_b32 m0, s53
	s_nop 0
	global_load_lds_dwordx4 v130, s[80:81]
	s_add_i32 m0, s53, 0x2000
	s_nop 0
	global_load_lds_dwordx4 v134, s[80:81]
	s_waitcnt vmcnt(6)
	s_waitcnt lgkmcnt(0)
	s_barrier
	s_setprio 1
	s_waitcnt lgkmcnt(0)
	v_mfma_f32_16x16x32_bf16 v[60:63], v[140:143], v[188:191], v[60:63]
	v_mfma_f32_16x16x32_bf16 v[56:59], v[150:153], v[188:191], v[56:59]
	v_mfma_f32_16x16x32_bf16 v[44:47], v[140:143], v[196:199], v[44:47]
	v_mfma_f32_16x16x32_bf16 v[40:43], v[150:153], v[196:199], v[40:43]
	v_mfma_f32_16x16x32_bf16 v[28:31], v[140:143], v[204:207], v[28:31]
	v_mfma_f32_16x16x32_bf16 v[24:27], v[150:153], v[204:207], v[24:27]
	v_mfma_f32_16x16x32_bf16 v[12:15], v[140:143], v[212:215], v[12:15]
	v_mfma_f32_16x16x32_bf16 v[8:11], v[150:153], v[212:215], v[8:11]
	v_mfma_f32_16x16x32_bf16 v[60:63], v[146:149], v[192:195], v[60:63]
	v_mfma_f32_16x16x32_bf16 v[56:59], v[154:157], v[192:195], v[56:59]
	v_mfma_f32_16x16x32_bf16 v[44:47], v[146:149], v[200:203], v[44:47]
	v_mfma_f32_16x16x32_bf16 v[40:43], v[154:157], v[200:203], v[40:43]
	v_mfma_f32_16x16x32_bf16 v[28:31], v[146:149], v[208:211], v[28:31]
	v_mfma_f32_16x16x32_bf16 v[24:27], v[154:157], v[208:211], v[24:27]
	v_mfma_f32_16x16x32_bf16 v[12:15], v[146:149], v[216:219], v[12:15]
	v_mfma_f32_16x16x32_bf16 v[8:11], v[154:157], v[216:219], v[8:11]
	s_setprio 0
	s_setprio 1
	v_mfma_f32_16x16x32_bf16 v[52:55], v[158:161], v[188:191], v[52:55]
	v_mfma_f32_16x16x32_bf16 v[48:51], v[166:169], v[188:191], v[48:51]
	v_mfma_f32_16x16x32_bf16 v[36:39], v[158:161], v[196:199], v[36:39]
	v_mfma_f32_16x16x32_bf16 v[32:35], v[166:169], v[196:199], v[32:35]
	v_mfma_f32_16x16x32_bf16 v[20:23], v[158:161], v[204:207], v[20:23]
	v_mfma_f32_16x16x32_bf16 v[16:19], v[166:169], v[204:207], v[16:19]
	v_mfma_f32_16x16x32_bf16 v[4:7], v[158:161], v[212:215], v[4:7]
	v_mfma_f32_16x16x32_bf16 v[0:3], v[166:169], v[212:215], v[0:3]
	v_mfma_f32_16x16x32_bf16 v[52:55], v[162:165], v[192:195], v[52:55]
	v_mfma_f32_16x16x32_bf16 v[48:51], v[170:173], v[192:195], v[48:51]
	v_mfma_f32_16x16x32_bf16 v[36:39], v[162:165], v[200:203], v[36:39]
	v_mfma_f32_16x16x32_bf16 v[32:35], v[170:173], v[200:203], v[32:35]
	v_mfma_f32_16x16x32_bf16 v[20:23], v[162:165], v[208:211], v[20:23]
	v_mfma_f32_16x16x32_bf16 v[16:19], v[170:173], v[208:211], v[16:19]
	v_mfma_f32_16x16x32_bf16 v[4:7], v[162:165], v[216:219], v[4:7]
	v_mfma_f32_16x16x32_bf16 v[0:3], v[170:173], v[216:219], v[0:3]
	s_setprio 0
	s_barrier
	s_add_i32 s53, 0, 0x18000
	s_add_i32 s80, 0, 0x1c000
	v_add_u32_e32 v154, s53, v144
	v_add_u32_e32 v170, s80, v144
	ds_read_b128 v[140:143], v154
	ds_read_b128 v[146:149], v154 offset:1024
	ds_read_b128 v[150:153], v154 offset:2048
	ds_read_b128 v[154:157], v154 offset:3072
	ds_read_b128 v[158:161], v170
	ds_read_b128 v[162:165], v170 offset:1024
	ds_read_b128 v[166:169], v170 offset:2048
	ds_read_b128 v[170:173], v170 offset:3072
	s_mov_b32 m0, s49
	s_nop 0
	global_load_lds_dwordx4 v128, s[30:31]
	s_mov_b32 m0, s15
	s_nop 0
	global_load_lds_dwordx4 v132, s[30:31]
	s_add_u32 s30, s30, 0x100000
	s_addc_u32 s31, s31, 0
	s_mov_b32 m0, s36
	ds_read_b128 v[188:191], v145 offset:32768
	ds_read_b128 v[192:195], v145 offset:33792
	ds_read_b128 v[196:199], v145 offset:34816
	ds_read_b128 v[200:203], v145 offset:35840
	ds_read_b128 v[204:207], v145 offset:36864
	ds_read_b128 v[208:211], v145 offset:37888
	ds_read_b128 v[212:215], v145 offset:38912
	ds_read_b128 v[216:219], v145 offset:39936
	global_load_lds_dwordx4 v128, s[30:31]
	s_mov_b32 m0, s50
	s_nop 0
	global_load_lds_dwordx4 v132, s[30:31]
	s_waitcnt vmcnt(8)
	s_waitcnt lgkmcnt(0)
	s_barrier
	s_setprio 1
	s_waitcnt lgkmcnt(0)
	v_mfma_f32_16x16x32_bf16 v[124:127], v[140:143], v[188:191], v[124:127]
	v_mfma_f32_16x16x32_bf16 v[120:123], v[150:153], v[188:191], v[120:123]
	v_mfma_f32_16x16x32_bf16 v[108:111], v[140:143], v[196:199], v[108:111]
	v_mfma_f32_16x16x32_bf16 v[104:107], v[150:153], v[196:199], v[104:107]
	v_mfma_f32_16x16x32_bf16 v[92:95], v[140:143], v[204:207], v[92:95]
	v_mfma_f32_16x16x32_bf16 v[88:91], v[150:153], v[204:207], v[88:91]
	v_mfma_f32_16x16x32_bf16 v[76:79], v[140:143], v[212:215], v[76:79]
	v_mfma_f32_16x16x32_bf16 v[72:75], v[150:153], v[212:215], v[72:75]
	v_mfma_f32_16x16x32_bf16 v[124:127], v[146:149], v[192:195], v[124:127]
	v_mfma_f32_16x16x32_bf16 v[120:123], v[154:157], v[192:195], v[120:123]
	v_mfma_f32_16x16x32_bf16 v[108:111], v[146:149], v[200:203], v[108:111]
	v_mfma_f32_16x16x32_bf16 v[104:107], v[154:157], v[200:203], v[104:107]
	v_mfma_f32_16x16x32_bf16 v[92:95], v[146:149], v[208:211], v[92:95]
	v_mfma_f32_16x16x32_bf16 v[88:91], v[154:157], v[208:211], v[88:91]
	v_mfma_f32_16x16x32_bf16 v[76:79], v[146:149], v[216:219], v[76:79]
	v_mfma_f32_16x16x32_bf16 v[72:75], v[154:157], v[216:219], v[72:75]
	s_setprio 0
	s_setprio 1
	v_mfma_f32_16x16x32_bf16 v[116:119], v[158:161], v[188:191], v[116:119]
	v_mfma_f32_16x16x32_bf16 v[112:115], v[166:169], v[188:191], v[112:115]
	v_mfma_f32_16x16x32_bf16 v[100:103], v[158:161], v[196:199], v[100:103]
	v_mfma_f32_16x16x32_bf16 v[96:99], v[166:169], v[196:199], v[96:99]
	v_mfma_f32_16x16x32_bf16 v[84:87], v[158:161], v[204:207], v[84:87]
	v_mfma_f32_16x16x32_bf16 v[80:83], v[166:169], v[204:207], v[80:83]
	v_mfma_f32_16x16x32_bf16 v[68:71], v[158:161], v[212:215], v[68:71]
	v_mfma_f32_16x16x32_bf16 v[64:67], v[166:169], v[212:215], v[64:67]
	v_mfma_f32_16x16x32_bf16 v[116:119], v[162:165], v[192:195], v[116:119]
	v_mfma_f32_16x16x32_bf16 v[112:115], v[170:173], v[192:195], v[112:115]
	v_mfma_f32_16x16x32_bf16 v[100:103], v[162:165], v[200:203], v[100:103]
	v_mfma_f32_16x16x32_bf16 v[96:99], v[170:173], v[200:203], v[96:99]
	v_mfma_f32_16x16x32_bf16 v[84:87], v[162:165], v[208:211], v[84:87]
	v_mfma_f32_16x16x32_bf16 v[80:83], v[170:173], v[208:211], v[80:83]
	v_mfma_f32_16x16x32_bf16 v[68:71], v[162:165], v[216:219], v[68:71]
	v_mfma_f32_16x16x32_bf16 v[64:67], v[170:173], v[216:219], v[64:67]
	s_setprio 0
	s_barrier
	s_add_i32 s30, s53, s43
	s_mov_b32 m0, s30
	ds_read_b128 v[188:191], v145 offset:49152
	ds_read_b128 v[192:195], v145 offset:50176
	ds_read_b128 v[196:199], v145 offset:51200
	ds_read_b128 v[200:203], v145 offset:52224
	ds_read_b128 v[204:207], v145 offset:53248
	ds_read_b128 v[208:211], v145 offset:54272
	ds_read_b128 v[212:215], v145 offset:55296
	ds_read_b128 v[216:219], v145 offset:56320
	global_load_lds_dwordx4 v130, s[38:39]
	s_add_i32 m0, s30, 0x2000
	s_add_u32 s6, s6, 0x100080
	s_addc_u32 s7, s7, 0
	s_add_i32 s30, s80, s43
	global_load_lds_dwordx4 v134, s[38:39]
	s_mov_b32 m0, s30
	s_nop 0
	global_load_lds_dwordx4 v130, s[6:7]
	s_add_i32 m0, s30, 0x2000
	s_nop 0
	global_load_lds_dwordx4 v134, s[6:7]
	s_waitcnt vmcnt(6)
	s_waitcnt lgkmcnt(0)
	s_barrier
	s_setprio 1
	s_waitcnt lgkmcnt(0)
	v_mfma_f32_16x16x32_bf16 v[60:63], v[140:143], v[188:191], v[60:63]
	v_mfma_f32_16x16x32_bf16 v[56:59], v[150:153], v[188:191], v[56:59]
	v_mfma_f32_16x16x32_bf16 v[44:47], v[140:143], v[196:199], v[44:47]
	v_mfma_f32_16x16x32_bf16 v[40:43], v[150:153], v[196:199], v[40:43]
	v_mfma_f32_16x16x32_bf16 v[28:31], v[140:143], v[204:207], v[28:31]
	v_mfma_f32_16x16x32_bf16 v[24:27], v[150:153], v[204:207], v[24:27]
	v_mfma_f32_16x16x32_bf16 v[12:15], v[140:143], v[212:215], v[12:15]
	v_mfma_f32_16x16x32_bf16 v[8:11], v[150:153], v[212:215], v[8:11]
	v_mfma_f32_16x16x32_bf16 v[60:63], v[146:149], v[192:195], v[60:63]
	v_mfma_f32_16x16x32_bf16 v[56:59], v[154:157], v[192:195], v[56:59]
	v_mfma_f32_16x16x32_bf16 v[44:47], v[146:149], v[200:203], v[44:47]
	v_mfma_f32_16x16x32_bf16 v[40:43], v[154:157], v[200:203], v[40:43]
	v_mfma_f32_16x16x32_bf16 v[28:31], v[146:149], v[208:211], v[28:31]
	v_mfma_f32_16x16x32_bf16 v[24:27], v[154:157], v[208:211], v[24:27]
	v_mfma_f32_16x16x32_bf16 v[12:15], v[146:149], v[216:219], v[12:15]
	v_mfma_f32_16x16x32_bf16 v[8:11], v[154:157], v[216:219], v[8:11]
	s_setprio 0
	s_setprio 1
	v_mfma_f32_16x16x32_bf16 v[52:55], v[158:161], v[188:191], v[52:55]
	v_mfma_f32_16x16x32_bf16 v[48:51], v[166:169], v[188:191], v[48:51]
	v_mfma_f32_16x16x32_bf16 v[36:39], v[158:161], v[196:199], v[36:39]
	v_mfma_f32_16x16x32_bf16 v[32:35], v[166:169], v[196:199], v[32:35]
	v_mfma_f32_16x16x32_bf16 v[20:23], v[158:161], v[204:207], v[20:23]
	v_mfma_f32_16x16x32_bf16 v[16:19], v[166:169], v[204:207], v[16:19]
	v_mfma_f32_16x16x32_bf16 v[4:7], v[158:161], v[212:215], v[4:7]
	v_mfma_f32_16x16x32_bf16 v[0:3], v[166:169], v[212:215], v[0:3]
	v_mfma_f32_16x16x32_bf16 v[52:55], v[162:165], v[192:195], v[52:55]
	v_mfma_f32_16x16x32_bf16 v[48:51], v[170:173], v[192:195], v[48:51]
	v_mfma_f32_16x16x32_bf16 v[36:39], v[162:165], v[200:203], v[36:39]
	v_mfma_f32_16x16x32_bf16 v[32:35], v[170:173], v[200:203], v[32:35]
	v_mfma_f32_16x16x32_bf16 v[20:23], v[162:165], v[208:211], v[20:23]
	v_mfma_f32_16x16x32_bf16 v[16:19], v[170:173], v[208:211], v[16:19]
	v_mfma_f32_16x16x32_bf16 v[4:7], v[162:165], v[216:219], v[4:7]
	v_mfma_f32_16x16x32_bf16 v[0:3], v[170:173], v[216:219], v[0:3]
	s_setprio 0
	s_barrier
	s_add_i32 s79, s79, 2
	s_add_u32 s4, s4, 0x100
	s_addc_u32 s5, s5, 0
	s_add_u32 s55, s55, 0x100
	s_addc_u32 s78, s78, 0
	s_cmp_gt_u32 s79, 61
	s_cbranch_scc0 .LBB0_367
	s_and_b64 vcc, exec, s[24:25]
	s_cbranch_vccz .LBB0_370
	s_barrier

.LBB0_687:
	s_add_u32 s26, s24, 0xffe00080
	s_addc_u32 s27, s25, -1
	s_add_i32 s53, 0, 0x10000
	s_cmp_eq_u32 s79, 60
	s_cselect_b32 s29, s7, s27
	s_cselect_b32 s28, s6, s26
	s_cselect_b32 s27, s19, s78
	s_cselect_b32 s26, s18, s57
	s_add_i32 s85, 0, 0x14000
	v_add_u32_e32 v152, s53, v142
	v_add_u32_e32 v168, s85, v142
	ds_read_b128 v[138:141], v152
	ds_read_b128 v[144:147], v152 offset:1024
	ds_read_b128 v[148:151], v152 offset:2048
	ds_read_b128 v[152:155], v152 offset:3072
	ds_read_b128 v[156:159], v168
	ds_read_b128 v[160:163], v168 offset:1024
	ds_read_b128 v[164:167], v168 offset:2048
	ds_read_b128 v[168:171], v168 offset:3072
	s_add_u32 s98, s24, 0xffe00000
	s_addc_u32 s99, s25, -1
	s_mov_b32 m0, s44
	s_nop 0
	global_load_lds_dwordx4 v132, s[98:99]
	s_mov_b32 m0, s48
	s_nop 0
	global_load_lds_dwordx4 v130, s[98:99]
	s_add_i32 m0, s31, 0xc000
	ds_read_b128 v[172:175], v143
	ds_read_b128 v[188:191], v143 offset:1024
	ds_read_b128 v[192:195], v143 offset:2048
	ds_read_b128 v[196:199], v143 offset:3072
	ds_read_b128 v[200:203], v143 offset:4096
	ds_read_b128 v[204:207], v143 offset:5120
	ds_read_b128 v[208:211], v143 offset:6144
	ds_read_b128 v[212:215], v143 offset:7168
	global_load_lds_dwordx4 v134, s[24:25]
	s_add_i32 m0, s31, 0xe000
	s_nop 0
	global_load_lds_dwordx4 v136, s[24:25]
	s_waitcnt vmcnt(8)
	s_waitcnt lgkmcnt(0)
	s_barrier
	s_setprio 1
	s_waitcnt lgkmcnt(0)
	v_mfma_f32_16x16x32_bf16 v[124:127], v[138:141], v[172:175], v[124:127]
	v_mfma_f32_16x16x32_bf16 v[120:123], v[148:151], v[172:175], v[120:123]
	v_mfma_f32_16x16x32_bf16 v[108:111], v[138:141], v[192:195], v[108:111]
	v_mfma_f32_16x16x32_bf16 v[104:107], v[148:151], v[192:195], v[104:107]
	v_mfma_f32_16x16x32_bf16 v[92:95], v[138:141], v[200:203], v[92:95]
	v_mfma_f32_16x16x32_bf16 v[88:91], v[148:151], v[200:203], v[88:91]
	v_mfma_f32_16x16x32_bf16 v[76:79], v[138:141], v[208:211], v[76:79]
	v_mfma_f32_16x16x32_bf16 v[72:75], v[148:151], v[208:211], v[72:75]
	v_mfma_f32_16x16x32_bf16 v[124:127], v[144:147], v[188:191], v[124:127]
	v_mfma_f32_16x16x32_bf16 v[120:123], v[152:155], v[188:191], v[120:123]
	v_mfma_f32_16x16x32_bf16 v[108:111], v[144:147], v[196:199], v[108:111]
	v_mfma_f32_16x16x32_bf16 v[104:107], v[152:155], v[196:199], v[104:107]
	v_mfma_f32_16x16x32_bf16 v[92:95], v[144:147], v[204:207], v[92:95]
	v_mfma_f32_16x16x32_bf16 v[88:91], v[152:155], v[204:207], v[88:91]
	v_mfma_f32_16x16x32_bf16 v[76:79], v[144:147], v[212:215], v[76:79]
	v_mfma_f32_16x16x32_bf16 v[72:75], v[152:155], v[212:215], v[72:75]
	s_setprio 0
	s_setprio 1
	v_mfma_f32_16x16x32_bf16 v[116:119], v[156:159], v[172:175], v[116:119]
	v_mfma_f32_16x16x32_bf16 v[112:115], v[164:167], v[172:175], v[112:115]
	v_mfma_f32_16x16x32_bf16 v[100:103], v[156:159], v[192:195], v[100:103]
	v_mfma_f32_16x16x32_bf16 v[96:99], v[164:167], v[192:195], v[96:99]
	v_mfma_f32_16x16x32_bf16 v[84:87], v[156:159], v[200:203], v[84:87]
	v_mfma_f32_16x16x32_bf16 v[80:83], v[164:167], v[200:203], v[80:83]
	v_mfma_f32_16x16x32_bf16 v[68:71], v[156:159], v[208:211], v[68:71]
	v_mfma_f32_16x16x32_bf16 v[64:67], v[164:167], v[208:211], v[64:67]
	v_mfma_f32_16x16x32_bf16 v[116:119], v[160:163], v[188:191], v[116:119]
	v_mfma_f32_16x16x32_bf16 v[112:115], v[168:171], v[188:191], v[112:115]
	v_mfma_f32_16x16x32_bf16 v[100:103], v[160:163], v[196:199], v[100:103]
	v_mfma_f32_16x16x32_bf16 v[96:99], v[168:171], v[196:199], v[96:99]
	v_mfma_f32_16x16x32_bf16 v[84:87], v[160:163], v[204:207], v[84:87]
	v_mfma_f32_16x16x32_bf16 v[80:83], v[168:171], v[204:207], v[80:83]
	v_mfma_f32_16x16x32_bf16 v[68:71], v[160:163], v[212:215], v[68:71]
	v_mfma_f32_16x16x32_bf16 v[64:67], v[168:171], v[212:215], v[64:67]
	s_setprio 0
	s_barrier
	s_add_i32 s53, s53, s30
	s_add_u32 s90, s26, 0x80
	s_addc_u32 s91, s27, 0
	s_mov_b32 m0, s53
	ds_read_b128 v[172:175], v143 offset:16384
	ds_read_b128 v[188:191], v143 offset:17408
	ds_read_b128 v[192:195], v143 offset:18432
	ds_read_b128 v[196:199], v143 offset:19456
	ds_read_b128 v[200:203], v143 offset:20480
	ds_read_b128 v[204:207], v143 offset:21504
	ds_read_b128 v[208:211], v143 offset:22528
	ds_read_b128 v[212:215], v143 offset:23552
	global_load_lds_dwordx4 v176, s[26:27]
	s_add_i32 m0, s53, 0x2000
	s_add_u32 s80, s26, 0x100000
	s_addc_u32 s81, s27, 0
	s_add_i32 s53, s85, s30
	global_load_lds_dwordx4 v128, s[26:27]
	s_mov_b32 m0, s53
	s_nop 0
	global_load_lds_dwordx4 v176, s[80:81]
	s_add_i32 m0, s53, 0x2000
	s_nop 0
	global_load_lds_dwordx4 v128, s[80:81]
	s_waitcnt vmcnt(6)
	s_waitcnt lgkmcnt(0)
	s_barrier
	s_setprio 1
	s_waitcnt lgkmcnt(0)
	v_mfma_f32_16x16x32_bf16 v[60:63], v[138:141], v[172:175], v[60:63]
	v_mfma_f32_16x16x32_bf16 v[56:59], v[148:151], v[172:175], v[56:59]
	v_mfma_f32_16x16x32_bf16 v[44:47], v[138:141], v[192:195], v[44:47]
	v_mfma_f32_16x16x32_bf16 v[40:43], v[148:151], v[192:195], v[40:43]
	v_mfma_f32_16x16x32_bf16 v[28:31], v[138:141], v[200:203], v[28:31]
	v_mfma_f32_16x16x32_bf16 v[24:27], v[148:151], v[200:203], v[24:27]
	v_mfma_f32_16x16x32_bf16 v[12:15], v[138:141], v[208:211], v[12:15]
	v_mfma_f32_16x16x32_bf16 v[8:11], v[148:151], v[208:211], v[8:11]
	v_mfma_f32_16x16x32_bf16 v[60:63], v[144:147], v[188:191], v[60:63]
	v_mfma_f32_16x16x32_bf16 v[56:59], v[152:155], v[188:191], v[56:59]
	v_mfma_f32_16x16x32_bf16 v[44:47], v[144:147], v[196:199], v[44:47]
	v_mfma_f32_16x16x32_bf16 v[40:43], v[152:155], v[196:199], v[40:43]
	v_mfma_f32_16x16x32_bf16 v[28:31], v[144:147], v[204:207], v[28:31]
	v_mfma_f32_16x16x32_bf16 v[24:27], v[152:155], v[204:207], v[24:27]
	v_mfma_f32_16x16x32_bf16 v[12:15], v[144:147], v[212:215], v[12:15]
	v_mfma_f32_16x16x32_bf16 v[8:11], v[152:155], v[212:215], v[8:11]
	s_setprio 0
	s_setprio 1
	v_mfma_f32_16x16x32_bf16 v[52:55], v[156:159], v[172:175], v[52:55]
	v_mfma_f32_16x16x32_bf16 v[48:51], v[164:167], v[172:175], v[48:51]
	v_mfma_f32_16x16x32_bf16 v[36:39], v[156:159], v[192:195], v[36:39]
	v_mfma_f32_16x16x32_bf16 v[32:35], v[164:167], v[192:195], v[32:35]
	v_mfma_f32_16x16x32_bf16 v[20:23], v[156:159], v[200:203], v[20:23]
	v_mfma_f32_16x16x32_bf16 v[16:19], v[164:167], v[200:203], v[16:19]
	v_mfma_f32_16x16x32_bf16 v[4:7], v[156:159], v[208:211], v[4:7]
	v_mfma_f32_16x16x32_bf16 v[0:3], v[164:167], v[208:211], v[0:3]
	v_mfma_f32_16x16x32_bf16 v[52:55], v[160:163], v[188:191], v[52:55]
	v_mfma_f32_16x16x32_bf16 v[48:51], v[168:171], v[188:191], v[48:51]
	v_mfma_f32_16x16x32_bf16 v[36:39], v[160:163], v[196:199], v[36:39]
	v_mfma_f32_16x16x32_bf16 v[32:35], v[168:171], v[196:199], v[32:35]
	v_mfma_f32_16x16x32_bf16 v[20:23], v[160:163], v[204:207], v[20:23]
	v_mfma_f32_16x16x32_bf16 v[16:19], v[168:171], v[204:207], v[16:19]
	v_mfma_f32_16x16x32_bf16 v[4:7], v[160:163], v[212:215], v[4:7]
	v_mfma_f32_16x16x32_bf16 v[0:3], v[168:171], v[212:215], v[0:3]
	s_setprio 0
	s_barrier
	s_add_i32 s53, 0, 0x18000
	s_add_i32 s80, 0, 0x1c000
	v_add_u32_e32 v152, s53, v142
	v_add_u32_e32 v168, s80, v142
	ds_read_b128 v[138:141], v152
	ds_read_b128 v[144:147], v152 offset:1024
	ds_read_b128 v[148:151], v152 offset:2048
	ds_read_b128 v[152:155], v152 offset:3072
	ds_read_b128 v[156:159], v168
	ds_read_b128 v[160:163], v168 offset:1024
	ds_read_b128 v[164:167], v168 offset:2048
	ds_read_b128 v[168:171], v168 offset:3072
	s_mov_b32 m0, s31
	s_nop 0
	global_load_lds_dwordx4 v132, s[28:29]
	s_mov_b32 m0, s34
	s_nop 0
	global_load_lds_dwordx4 v130, s[28:29]
	s_add_u32 s28, s28, 0x200000
	s_addc_u32 s29, s29, 0
	s_mov_b32 m0, s35
	ds_read_b128 v[172:175], v143 offset:32768
	ds_read_b128 v[188:191], v143 offset:33792
	ds_read_b128 v[192:195], v143 offset:34816
	ds_read_b128 v[196:199], v143 offset:35840
	ds_read_b128 v[200:203], v143 offset:36864
	ds_read_b128 v[204:207], v143 offset:37888
	ds_read_b128 v[208:211], v143 offset:38912
	ds_read_b128 v[212:215], v143 offset:39936
	global_load_lds_dwordx4 v132, s[28:29]
	s_mov_b32 m0, s36
	s_nop 0
	global_load_lds_dwordx4 v130, s[28:29]
	s_waitcnt vmcnt(8)
	s_waitcnt lgkmcnt(0)
	s_barrier
	s_setprio 1
	s_waitcnt lgkmcnt(0)
	v_mfma_f32_16x16x32_bf16 v[124:127], v[138:141], v[172:175], v[124:127]
	v_mfma_f32_16x16x32_bf16 v[120:123], v[148:151], v[172:175], v[120:123]
	v_mfma_f32_16x16x32_bf16 v[108:111], v[138:141], v[192:195], v[108:111]
	v_mfma_f32_16x16x32_bf16 v[104:107], v[148:151], v[192:195], v[104:107]
	v_mfma_f32_16x16x32_bf16 v[92:95], v[138:141], v[200:203], v[92:95]
	v_mfma_f32_16x16x32_bf16 v[88:91], v[148:151], v[200:203], v[88:91]
	v_mfma_f32_16x16x32_bf16 v[76:79], v[138:141], v[208:211], v[76:79]
	v_mfma_f32_16x16x32_bf16 v[72:75], v[148:151], v[208:211], v[72:75]
	v_mfma_f32_16x16x32_bf16 v[124:127], v[144:147], v[188:191], v[124:127]
	v_mfma_f32_16x16x32_bf16 v[120:123], v[152:155], v[188:191], v[120:123]
	v_mfma_f32_16x16x32_bf16 v[108:111], v[144:147], v[196:199], v[108:111]
	v_mfma_f32_16x16x32_bf16 v[104:107], v[152:155], v[196:199], v[104:107]
	v_mfma_f32_16x16x32_bf16 v[92:95], v[144:147], v[204:207], v[92:95]
	v_mfma_f32_16x16x32_bf16 v[88:91], v[152:155], v[204:207], v[88:91]
	v_mfma_f32_16x16x32_bf16 v[76:79], v[144:147], v[212:215], v[76:79]
	v_mfma_f32_16x16x32_bf16 v[72:75], v[152:155], v[212:215], v[72:75]
	s_setprio 0
	s_setprio 1
	v_mfma_f32_16x16x32_bf16 v[116:119], v[156:159], v[172:175], v[116:119]
	v_mfma_f32_16x16x32_bf16 v[112:115], v[164:167], v[172:175], v[112:115]
	v_mfma_f32_16x16x32_bf16 v[100:103], v[156:159], v[192:195], v[100:103]
	v_mfma_f32_16x16x32_bf16 v[96:99], v[164:167], v[192:195], v[96:99]
	v_mfma_f32_16x16x32_bf16 v[84:87], v[156:159], v[200:203], v[84:87]
	v_mfma_f32_16x16x32_bf16 v[80:83], v[164:167], v[200:203], v[80:83]
	v_mfma_f32_16x16x32_bf16 v[68:71], v[156:159], v[208:211], v[68:71]
	v_mfma_f32_16x16x32_bf16 v[64:67], v[164:167], v[208:211], v[64:67]
	v_mfma_f32_16x16x32_bf16 v[116:119], v[160:163], v[188:191], v[116:119]
	v_mfma_f32_16x16x32_bf16 v[112:115], v[168:171], v[188:191], v[112:115]
	v_mfma_f32_16x16x32_bf16 v[100:103], v[160:163], v[196:199], v[100:103]
	v_mfma_f32_16x16x32_bf16 v[96:99], v[168:171], v[196:199], v[96:99]
	v_mfma_f32_16x16x32_bf16 v[84:87], v[160:163], v[204:207], v[84:87]
	v_mfma_f32_16x16x32_bf16 v[80:83], v[168:171], v[204:207], v[80:83]
	v_mfma_f32_16x16x32_bf16 v[68:71], v[160:163], v[212:215], v[68:71]
	v_mfma_f32_16x16x32_bf16 v[64:67], v[168:171], v[212:215], v[64:67]
	s_setprio 0
	s_barrier
	s_add_i32 s28, s53, s30
	s_mov_b32 m0, s28
	ds_read_b128 v[172:175], v143 offset:49152
	ds_read_b128 v[188:191], v143 offset:50176
	ds_read_b128 v[192:195], v143 offset:51200
	ds_read_b128 v[196:199], v143 offset:52224
	ds_read_b128 v[200:203], v143 offset:53248
	ds_read_b128 v[204:207], v143 offset:54272
	ds_read_b128 v[208:211], v143 offset:55296
	ds_read_b128 v[212:215], v143 offset:56320
	global_load_lds_dwordx4 v176, s[90:91]
	s_add_i32 m0, s28, 0x2000
	s_add_u32 s26, s26, 0x100080
	s_addc_u32 s27, s27, 0
	s_add_i32 s28, s80, s30
	global_load_lds_dwordx4 v128, s[90:91]
	s_mov_b32 m0, s28
	s_nop 0
	global_load_lds_dwordx4 v176, s[26:27]
	s_add_i32 m0, s28, 0x2000
	s_nop 0
	global_load_lds_dwordx4 v128, s[26:27]
	s_waitcnt vmcnt(6)
	s_waitcnt lgkmcnt(0)
	s_barrier
	s_setprio 1
	s_waitcnt lgkmcnt(0)
	v_mfma_f32_16x16x32_bf16 v[60:63], v[138:141], v[172:175], v[60:63]
	v_mfma_f32_16x16x32_bf16 v[56:59], v[148:151], v[172:175], v[56:59]
	v_mfma_f32_16x16x32_bf16 v[44:47], v[138:141], v[192:195], v[44:47]
	v_mfma_f32_16x16x32_bf16 v[40:43], v[148:151], v[192:195], v[40:43]
	v_mfma_f32_16x16x32_bf16 v[28:31], v[138:141], v[200:203], v[28:31]
	v_mfma_f32_16x16x32_bf16 v[24:27], v[148:151], v[200:203], v[24:27]
	v_mfma_f32_16x16x32_bf16 v[12:15], v[138:141], v[208:211], v[12:15]
	v_mfma_f32_16x16x32_bf16 v[8:11], v[148:151], v[208:211], v[8:11]
	v_mfma_f32_16x16x32_bf16 v[60:63], v[144:147], v[188:191], v[60:63]
	v_mfma_f32_16x16x32_bf16 v[56:59], v[152:155], v[188:191], v[56:59]
	v_mfma_f32_16x16x32_bf16 v[44:47], v[144:147], v[196:199], v[44:47]
	v_mfma_f32_16x16x32_bf16 v[40:43], v[152:155], v[196:199], v[40:43]
	v_mfma_f32_16x16x32_bf16 v[28:31], v[144:147], v[204:207], v[28:31]
	v_mfma_f32_16x16x32_bf16 v[24:27], v[152:155], v[204:207], v[24:27]
	v_mfma_f32_16x16x32_bf16 v[12:15], v[144:147], v[212:215], v[12:15]
	v_mfma_f32_16x16x32_bf16 v[8:11], v[152:155], v[212:215], v[8:11]
	s_setprio 0
	s_setprio 1
	v_mfma_f32_16x16x32_bf16 v[52:55], v[156:159], v[172:175], v[52:55]
	v_mfma_f32_16x16x32_bf16 v[48:51], v[164:167], v[172:175], v[48:51]
	v_mfma_f32_16x16x32_bf16 v[36:39], v[156:159], v[192:195], v[36:39]
	v_mfma_f32_16x16x32_bf16 v[32:35], v[164:167], v[192:195], v[32:35]
	v_mfma_f32_16x16x32_bf16 v[20:23], v[156:159], v[200:203], v[20:23]
	v_mfma_f32_16x16x32_bf16 v[16:19], v[164:167], v[200:203], v[16:19]
	v_mfma_f32_16x16x32_bf16 v[4:7], v[156:159], v[208:211], v[4:7]
	v_mfma_f32_16x16x32_bf16 v[0:3], v[164:167], v[208:211], v[0:3]
	v_mfma_f32_16x16x32_bf16 v[52:55], v[160:163], v[188:191], v[52:55]
	v_mfma_f32_16x16x32_bf16 v[48:51], v[168:171], v[188:191], v[48:51]
	v_mfma_f32_16x16x32_bf16 v[36:39], v[160:163], v[196:199], v[36:39]
	v_mfma_f32_16x16x32_bf16 v[32:35], v[168:171], v[196:199], v[32:35]
	v_mfma_f32_16x16x32_bf16 v[20:23], v[160:163], v[204:207], v[20:23]
	v_mfma_f32_16x16x32_bf16 v[16:19], v[168:171], v[204:207], v[16:19]
	v_mfma_f32_16x16x32_bf16 v[4:7], v[160:163], v[212:215], v[4:7]
	v_mfma_f32_16x16x32_bf16 v[0:3], v[168:171], v[212:215], v[0:3]
	s_setprio 0
	s_barrier
	s_add_i32 s79, s79, 2
	s_add_u32 s24, s24, 0x100
	s_addc_u32 s25, s25, 0
	s_add_u32 s57, s57, 0x100
	s_addc_u32 s78, s78, 0
	s_cmp_gt_u32 s79, 61
	s_cbranch_scc0 .LBB0_687
	s_and_b64 vcc, exec, s[4:5]
	s_cbranch_vccz .LBB0_690
	s_barrier

.LBB0_761:
	s_add_u32 s34, s30, 0xfffc0080
	s_addc_u32 s35, s31, -1
	s_add_i32 s38, 0, 0x10000
	s_cmp_eq_u32 s79, 12
	s_cselect_b32 s49, s27, s35
	s_cselect_b32 s48, s26, s34
	v_add_u32_e32 v142, s38, v144
	s_cselect_b32 s35, s29, s78
	s_cselect_b32 s34, s28, s55
	s_add_i32 s39, 0, 0x14000
	ds_read_b128 v[138:141], v142
	ds_read_b128 v[146:149], v142 offset:1024
	ds_read_b128 v[150:153], v142 offset:2048
	ds_read_b128 v[154:157], v142 offset:3072
	v_add_u32_e32 v142, s39, v144
	ds_read_b128 v[158:161], v142
	ds_read_b128 v[162:165], v142 offset:1024
	ds_read_b128 v[166:169], v142 offset:2048
	ds_read_b128 v[170:173], v142 offset:3072
	s_add_u32 s98, s30, 0xfffc0000
	s_addc_u32 s99, s31, -1
	s_mov_b32 m0, s93
	s_nop 0
	global_load_lds_dwordx4 v128, s[98:99]
	s_mov_b32 m0, s85
	s_nop 0
	global_load_lds_dwordx4 v130, s[98:99]
	s_add_i32 m0, s10, 0xc000
	ds_read_b128 v[178:181], v145
	ds_read_b128 v[182:185], v145 offset:1024
	ds_read_b128 v[188:191], v145 offset:2048
	ds_read_b128 v[192:195], v145 offset:3072
	ds_read_b128 v[196:199], v145 offset:4096
	ds_read_b128 v[200:203], v145 offset:5120
	ds_read_b128 v[204:207], v145 offset:6144
	ds_read_b128 v[208:211], v145 offset:7168
	global_load_lds_dwordx4 v134, s[30:31]
	s_add_i32 m0, s10, 0xe000
	s_nop 0
	global_load_lds_dwordx4 v136, s[30:31]
	s_waitcnt vmcnt(8)
	s_waitcnt lgkmcnt(0)
	s_barrier
	s_setprio 1
	s_waitcnt lgkmcnt(0)
	v_mfma_f32_16x16x32_bf16 v[124:127], v[138:141], v[178:181], v[124:127]
	v_mfma_f32_16x16x32_bf16 v[112:115], v[150:153], v[178:181], v[112:115]
	v_mfma_f32_16x16x32_bf16 v[108:111], v[138:141], v[188:191], v[108:111]
	v_mfma_f32_16x16x32_bf16 v[96:99], v[150:153], v[188:191], v[96:99]
	v_mfma_f32_16x16x32_bf16 v[92:95], v[138:141], v[196:199], v[92:95]
	v_mfma_f32_16x16x32_bf16 v[80:83], v[150:153], v[196:199], v[80:83]
	v_mfma_f32_16x16x32_bf16 v[76:79], v[138:141], v[204:207], v[76:79]
	v_mfma_f32_16x16x32_bf16 v[64:67], v[150:153], v[204:207], v[64:67]
	v_mfma_f32_16x16x32_bf16 v[124:127], v[146:149], v[182:185], v[124:127]
	v_mfma_f32_16x16x32_bf16 v[112:115], v[154:157], v[182:185], v[112:115]
	v_mfma_f32_16x16x32_bf16 v[108:111], v[146:149], v[192:195], v[108:111]
	v_mfma_f32_16x16x32_bf16 v[96:99], v[154:157], v[192:195], v[96:99]
	v_mfma_f32_16x16x32_bf16 v[92:95], v[146:149], v[200:203], v[92:95]
	v_mfma_f32_16x16x32_bf16 v[80:83], v[154:157], v[200:203], v[80:83]
	v_mfma_f32_16x16x32_bf16 v[76:79], v[146:149], v[208:211], v[76:79]
	v_mfma_f32_16x16x32_bf16 v[64:67], v[154:157], v[208:211], v[64:67]
	s_setprio 0
	s_setprio 1
	v_mfma_f32_16x16x32_bf16 v[120:123], v[158:161], v[178:181], v[120:123]
	v_mfma_f32_16x16x32_bf16 v[116:119], v[166:169], v[178:181], v[116:119]
	v_mfma_f32_16x16x32_bf16 v[104:107], v[158:161], v[188:191], v[104:107]
	v_mfma_f32_16x16x32_bf16 v[100:103], v[166:169], v[188:191], v[100:103]
	v_mfma_f32_16x16x32_bf16 v[88:91], v[158:161], v[196:199], v[88:91]
	v_mfma_f32_16x16x32_bf16 v[84:87], v[166:169], v[196:199], v[84:87]
	v_mfma_f32_16x16x32_bf16 v[72:75], v[158:161], v[204:207], v[72:75]
	v_mfma_f32_16x16x32_bf16 v[68:71], v[166:169], v[204:207], v[68:71]
	v_mfma_f32_16x16x32_bf16 v[120:123], v[162:165], v[182:185], v[120:123]
	v_mfma_f32_16x16x32_bf16 v[116:119], v[170:173], v[182:185], v[116:119]
	v_mfma_f32_16x16x32_bf16 v[104:107], v[162:165], v[192:195], v[104:107]
	v_mfma_f32_16x16x32_bf16 v[100:103], v[170:173], v[192:195], v[100:103]
	v_mfma_f32_16x16x32_bf16 v[88:91], v[162:165], v[200:203], v[88:91]
	v_mfma_f32_16x16x32_bf16 v[84:87], v[170:173], v[200:203], v[84:87]
	v_mfma_f32_16x16x32_bf16 v[72:75], v[162:165], v[208:211], v[72:75]
	v_mfma_f32_16x16x32_bf16 v[68:71], v[170:173], v[208:211], v[68:71]
	s_setprio 0
	s_barrier
	s_add_i32 s38, s38, s44
	s_add_u32 s90, s34, 0x80
	s_addc_u32 s91, s35, 0
	s_mov_b32 m0, s38
	ds_read_b128 v[178:181], v145 offset:16384
	ds_read_b128 v[182:185], v145 offset:17408
	ds_read_b128 v[188:191], v145 offset:18432
	ds_read_b128 v[192:195], v145 offset:19456
	ds_read_b128 v[196:199], v145 offset:20480
	ds_read_b128 v[200:203], v145 offset:21504
	ds_read_b128 v[204:207], v145 offset:22528
	ds_read_b128 v[208:211], v145 offset:23552
	global_load_lds_dwordx4 v176, s[34:35]
	s_add_i32 m0, s38, 0x2000
	s_add_u32 s80, s34, 0x40000
	s_addc_u32 s81, s35, 0
	s_add_i32 s38, s39, s44
	global_load_lds_dwordx4 v132, s[34:35]
	s_mov_b32 m0, s38
	s_nop 0
	global_load_lds_dwordx4 v176, s[80:81]
	s_add_i32 m0, s38, 0x2000
	s_nop 0
	global_load_lds_dwordx4 v132, s[80:81]
	s_waitcnt vmcnt(6)
	s_waitcnt lgkmcnt(0)
	s_barrier
	s_setprio 1
	s_waitcnt lgkmcnt(0)
	v_mfma_f32_16x16x32_bf16 v[60:63], v[138:141], v[178:181], v[60:63]
	v_mfma_f32_16x16x32_bf16 v[48:51], v[150:153], v[178:181], v[48:51]
	v_mfma_f32_16x16x32_bf16 v[44:47], v[138:141], v[188:191], v[44:47]
	v_mfma_f32_16x16x32_bf16 v[32:35], v[150:153], v[188:191], v[32:35]
	v_mfma_f32_16x16x32_bf16 v[28:31], v[138:141], v[196:199], v[28:31]
	v_mfma_f32_16x16x32_bf16 v[16:19], v[150:153], v[196:199], v[16:19]
	v_mfma_f32_16x16x32_bf16 v[12:15], v[138:141], v[204:207], v[12:15]
	v_mfma_f32_16x16x32_bf16 v[8:11], v[150:153], v[204:207], v[8:11]
	v_mfma_f32_16x16x32_bf16 v[60:63], v[146:149], v[182:185], v[60:63]
	v_mfma_f32_16x16x32_bf16 v[48:51], v[154:157], v[182:185], v[48:51]
	v_mfma_f32_16x16x32_bf16 v[44:47], v[146:149], v[192:195], v[44:47]
	v_mfma_f32_16x16x32_bf16 v[32:35], v[154:157], v[192:195], v[32:35]
	v_mfma_f32_16x16x32_bf16 v[28:31], v[146:149], v[200:203], v[28:31]
	v_mfma_f32_16x16x32_bf16 v[16:19], v[154:157], v[200:203], v[16:19]
	v_mfma_f32_16x16x32_bf16 v[12:15], v[146:149], v[208:211], v[12:15]
	v_mfma_f32_16x16x32_bf16 v[8:11], v[154:157], v[208:211], v[8:11]
	s_setprio 0
	s_setprio 1
	v_mfma_f32_16x16x32_bf16 v[56:59], v[158:161], v[178:181], v[56:59]
	v_mfma_f32_16x16x32_bf16 v[52:55], v[166:169], v[178:181], v[52:55]
	v_mfma_f32_16x16x32_bf16 v[40:43], v[158:161], v[188:191], v[40:43]
	v_mfma_f32_16x16x32_bf16 v[36:39], v[166:169], v[188:191], v[36:39]
	v_mfma_f32_16x16x32_bf16 v[24:27], v[158:161], v[196:199], v[24:27]
	v_mfma_f32_16x16x32_bf16 v[20:23], v[166:169], v[196:199], v[20:23]
	v_mfma_f32_16x16x32_bf16 v[4:7], v[158:161], v[204:207], v[4:7]
	v_mfma_f32_16x16x32_bf16 v[0:3], v[166:169], v[204:207], v[0:3]
	v_mfma_f32_16x16x32_bf16 v[56:59], v[162:165], v[182:185], v[56:59]
	v_mfma_f32_16x16x32_bf16 v[52:55], v[170:173], v[182:185], v[52:55]
	v_mfma_f32_16x16x32_bf16 v[40:43], v[162:165], v[192:195], v[40:43]
	v_mfma_f32_16x16x32_bf16 v[36:39], v[170:173], v[192:195], v[36:39]
	v_mfma_f32_16x16x32_bf16 v[24:27], v[162:165], v[200:203], v[24:27]
	v_mfma_f32_16x16x32_bf16 v[20:23], v[170:173], v[200:203], v[20:23]
	v_mfma_f32_16x16x32_bf16 v[4:7], v[162:165], v[208:211], v[4:7]
	v_mfma_f32_16x16x32_bf16 v[0:3], v[170:173], v[208:211], v[0:3]
	s_setprio 0
	s_barrier
	s_add_i32 s38, 0, 0x18000
	s_add_i32 s39, 0, 0x1c000
	v_add_u32_e32 v154, s38, v144
	v_add_u32_e32 v170, s39, v144
	ds_read_b128 v[138:141], v154
	ds_read_b128 v[146:149], v154 offset:1024
	ds_read_b128 v[150:153], v154 offset:2048
	ds_read_b128 v[154:157], v154 offset:3072
	ds_read_b128 v[158:161], v170
	ds_read_b128 v[162:165], v170 offset:1024
	ds_read_b128 v[166:169], v170 offset:2048
	ds_read_b128 v[170:173], v170 offset:3072
	s_mov_b32 m0, s10
	s_nop 0
	global_load_lds_dwordx4 v128, s[48:49]
	s_mov_b32 m0, s11
	s_nop 0
	global_load_lds_dwordx4 v130, s[48:49]
	s_add_u32 s48, s48, 0x40000
	s_addc_u32 s49, s49, 0
	s_mov_b32 m0, s8
	ds_read_b128 v[178:181], v145 offset:32768
	ds_read_b128 v[182:185], v145 offset:33792
	ds_read_b128 v[188:191], v145 offset:34816
	ds_read_b128 v[192:195], v145 offset:35840
	ds_read_b128 v[196:199], v145 offset:36864
	ds_read_b128 v[200:203], v145 offset:37888
	ds_read_b128 v[204:207], v145 offset:38912
	ds_read_b128 v[208:211], v145 offset:39936
	global_load_lds_dwordx4 v128, s[48:49]
	s_mov_b32 m0, s9
	s_nop 0
	global_load_lds_dwordx4 v130, s[48:49]
	s_waitcnt vmcnt(8)
	s_waitcnt lgkmcnt(0)
	s_barrier
	s_setprio 1
	s_waitcnt lgkmcnt(0)
	v_mfma_f32_16x16x32_bf16 v[124:127], v[138:141], v[178:181], v[124:127]
	v_mfma_f32_16x16x32_bf16 v[112:115], v[150:153], v[178:181], v[112:115]
	v_mfma_f32_16x16x32_bf16 v[108:111], v[138:141], v[188:191], v[108:111]
	v_mfma_f32_16x16x32_bf16 v[96:99], v[150:153], v[188:191], v[96:99]
	v_mfma_f32_16x16x32_bf16 v[92:95], v[138:141], v[196:199], v[92:95]
	v_mfma_f32_16x16x32_bf16 v[80:83], v[150:153], v[196:199], v[80:83]
	v_mfma_f32_16x16x32_bf16 v[76:79], v[138:141], v[204:207], v[76:79]
	v_mfma_f32_16x16x32_bf16 v[64:67], v[150:153], v[204:207], v[64:67]
	v_mfma_f32_16x16x32_bf16 v[124:127], v[146:149], v[182:185], v[124:127]
	v_mfma_f32_16x16x32_bf16 v[112:115], v[154:157], v[182:185], v[112:115]
	v_mfma_f32_16x16x32_bf16 v[108:111], v[146:149], v[192:195], v[108:111]
	v_mfma_f32_16x16x32_bf16 v[96:99], v[154:157], v[192:195], v[96:99]
	v_mfma_f32_16x16x32_bf16 v[92:95], v[146:149], v[200:203], v[92:95]
	v_mfma_f32_16x16x32_bf16 v[80:83], v[154:157], v[200:203], v[80:83]
	v_mfma_f32_16x16x32_bf16 v[76:79], v[146:149], v[208:211], v[76:79]
	v_mfma_f32_16x16x32_bf16 v[64:67], v[154:157], v[208:211], v[64:67]
	s_setprio 0
	s_setprio 1
	v_mfma_f32_16x16x32_bf16 v[120:123], v[158:161], v[178:181], v[120:123]
	v_mfma_f32_16x16x32_bf16 v[116:119], v[166:169], v[178:181], v[116:119]
	v_mfma_f32_16x16x32_bf16 v[104:107], v[158:161], v[188:191], v[104:107]
	v_mfma_f32_16x16x32_bf16 v[100:103], v[166:169], v[188:191], v[100:103]
	v_mfma_f32_16x16x32_bf16 v[88:91], v[158:161], v[196:199], v[88:91]
	v_mfma_f32_16x16x32_bf16 v[84:87], v[166:169], v[196:199], v[84:87]
	v_mfma_f32_16x16x32_bf16 v[72:75], v[158:161], v[204:207], v[72:75]
	v_mfma_f32_16x16x32_bf16 v[68:71], v[166:169], v[204:207], v[68:71]
	v_mfma_f32_16x16x32_bf16 v[120:123], v[162:165], v[182:185], v[120:123]
	v_mfma_f32_16x16x32_bf16 v[116:119], v[170:173], v[182:185], v[116:119]
	v_mfma_f32_16x16x32_bf16 v[104:107], v[162:165], v[192:195], v[104:107]
	v_mfma_f32_16x16x32_bf16 v[100:103], v[170:173], v[192:195], v[100:103]
	v_mfma_f32_16x16x32_bf16 v[88:91], v[162:165], v[200:203], v[88:91]
	v_mfma_f32_16x16x32_bf16 v[84:87], v[170:173], v[200:203], v[84:87]
	v_mfma_f32_16x16x32_bf16 v[72:75], v[162:165], v[208:211], v[72:75]
	v_mfma_f32_16x16x32_bf16 v[68:71], v[170:173], v[208:211], v[68:71]
	s_setprio 0
	s_barrier
	s_add_i32 s38, s38, s44
	s_mov_b32 m0, s38
	ds_read_b128 v[178:181], v145 offset:49152
	ds_read_b128 v[182:185], v145 offset:50176
	ds_read_b128 v[188:191], v145 offset:51200
	ds_read_b128 v[192:195], v145 offset:52224
	ds_read_b128 v[196:199], v145 offset:53248
	ds_read_b128 v[200:203], v145 offset:54272
	ds_read_b128 v[204:207], v145 offset:55296
	ds_read_b128 v[208:211], v145 offset:56320
	global_load_lds_dwordx4 v176, s[90:91]
	s_add_i32 m0, s38, 0x2000
	s_add_u32 s34, s34, 0x40080
	s_addc_u32 s35, s35, 0
	s_add_i32 s38, s39, s44
	global_load_lds_dwordx4 v132, s[90:91]
	s_mov_b32 m0, s38
	s_nop 0
	global_load_lds_dwordx4 v176, s[34:35]
	s_add_i32 m0, s38, 0x2000
	s_nop 0
	global_load_lds_dwordx4 v132, s[34:35]
	s_waitcnt vmcnt(6)
	s_waitcnt lgkmcnt(0)
	s_barrier
	s_setprio 1
	s_waitcnt lgkmcnt(0)
	v_mfma_f32_16x16x32_bf16 v[60:63], v[138:141], v[178:181], v[60:63]
	v_mfma_f32_16x16x32_bf16 v[48:51], v[150:153], v[178:181], v[48:51]
	v_mfma_f32_16x16x32_bf16 v[44:47], v[138:141], v[188:191], v[44:47]
	v_mfma_f32_16x16x32_bf16 v[32:35], v[150:153], v[188:191], v[32:35]
	v_mfma_f32_16x16x32_bf16 v[28:31], v[138:141], v[196:199], v[28:31]
	v_mfma_f32_16x16x32_bf16 v[16:19], v[150:153], v[196:199], v[16:19]
	v_mfma_f32_16x16x32_bf16 v[12:15], v[138:141], v[204:207], v[12:15]
	v_mfma_f32_16x16x32_bf16 v[8:11], v[150:153], v[204:207], v[8:11]
	v_mfma_f32_16x16x32_bf16 v[60:63], v[146:149], v[182:185], v[60:63]
	v_mfma_f32_16x16x32_bf16 v[48:51], v[154:157], v[182:185], v[48:51]
	v_mfma_f32_16x16x32_bf16 v[44:47], v[146:149], v[192:195], v[44:47]
	v_mfma_f32_16x16x32_bf16 v[32:35], v[154:157], v[192:195], v[32:35]
	v_mfma_f32_16x16x32_bf16 v[28:31], v[146:149], v[200:203], v[28:31]
	v_mfma_f32_16x16x32_bf16 v[16:19], v[154:157], v[200:203], v[16:19]
	v_mfma_f32_16x16x32_bf16 v[12:15], v[146:149], v[208:211], v[12:15]
	v_mfma_f32_16x16x32_bf16 v[8:11], v[154:157], v[208:211], v[8:11]
	s_setprio 0
	s_setprio 1
	v_mfma_f32_16x16x32_bf16 v[56:59], v[158:161], v[178:181], v[56:59]
	v_mfma_f32_16x16x32_bf16 v[52:55], v[166:169], v[178:181], v[52:55]
	v_mfma_f32_16x16x32_bf16 v[40:43], v[158:161], v[188:191], v[40:43]
	v_mfma_f32_16x16x32_bf16 v[36:39], v[166:169], v[188:191], v[36:39]
	v_mfma_f32_16x16x32_bf16 v[24:27], v[158:161], v[196:199], v[24:27]
	v_mfma_f32_16x16x32_bf16 v[20:23], v[166:169], v[196:199], v[20:23]
	v_mfma_f32_16x16x32_bf16 v[4:7], v[158:161], v[204:207], v[4:7]
	v_mfma_f32_16x16x32_bf16 v[0:3], v[166:169], v[204:207], v[0:3]
	v_mfma_f32_16x16x32_bf16 v[56:59], v[162:165], v[182:185], v[56:59]
	v_mfma_f32_16x16x32_bf16 v[52:55], v[170:173], v[182:185], v[52:55]
	v_mfma_f32_16x16x32_bf16 v[40:43], v[162:165], v[192:195], v[40:43]
	v_mfma_f32_16x16x32_bf16 v[36:39], v[170:173], v[192:195], v[36:39]
	v_mfma_f32_16x16x32_bf16 v[24:27], v[162:165], v[200:203], v[24:27]
	v_mfma_f32_16x16x32_bf16 v[20:23], v[170:173], v[200:203], v[20:23]
	v_mfma_f32_16x16x32_bf16 v[4:7], v[162:165], v[208:211], v[4:7]
	v_mfma_f32_16x16x32_bf16 v[0:3], v[170:173], v[208:211], v[0:3]
	s_setprio 0
	s_barrier
	s_add_i32 s79, s79, 2
	s_add_u32 s30, s30, 0x100
	s_addc_u32 s31, s31, 0
	s_add_u32 s55, s55, 0x100
	s_addc_u32 s78, s78, 0
	s_cmp_gt_u32 s79, 13
	s_cbranch_scc0 .LBB0_761
	s_and_b64 vcc, exec, s[18:19]
	s_cbranch_vccz .LBB0_764
	s_barrier

.LBB0_921:
	s_add_u32 s24, s22, 0xfff00080
	s_addc_u32 s25, s23, -1
	s_add_i32 s38, 0, 0x10000
	s_cmp_eq_u32 s79, 60
	s_cselect_b32 s27, s19, s25
	s_cselect_b32 s26, s18, s24
	s_cselect_b32 s25, s21, s78
	s_cselect_b32 s24, s20, s55
	s_add_i32 s39, 0, 0x14000
	v_add_u32_e32 v140, s38, v160
	v_add_u32_e32 v158, s39, v160
	ds_read_b128 v[120:123], v140
	ds_read_b128 v[132:135], v140 offset:1024
	ds_read_b128 v[136:139], v140 offset:2048
	ds_read_b128 v[140:143], v140 offset:3072
	ds_read_b128 v[154:157], v158
	ds_read_b128 v[162:165], v158 offset:1024
	ds_read_b128 v[166:169], v158 offset:2048
	ds_read_b128 v[170:173], v158 offset:3072
	s_add_u32 s96, s22, 0xfff00000
	s_addc_u32 s97, s23, -1
	s_mov_b32 m0, s49
	s_nop 0
	global_load_lds_dwordx4 v144, s[96:97]
	s_mov_b32 m0, s50
	s_nop 0
	global_load_lds_dwordx4 v146, s[96:97]
	s_add_i32 m0, s34, 0xc000
	ds_read_b128 v[178:181], v161
	ds_read_b128 v[182:185], v161 offset:1024
	ds_read_b128 v[188:191], v161 offset:2048
	ds_read_b128 v[192:195], v161 offset:3072
	ds_read_b128 v[196:199], v161 offset:4096
	ds_read_b128 v[200:203], v161 offset:5120
	ds_read_b128 v[204:207], v161 offset:6144
	ds_read_b128 v[208:211], v161 offset:7168
	global_load_lds_dwordx4 v150, s[22:23]
	s_add_i32 m0, s34, 0xe000
	s_nop 0
	global_load_lds_dwordx4 v152, s[22:23]
	s_waitcnt vmcnt(8)
	s_waitcnt lgkmcnt(0)
	s_barrier
	s_setprio 1
	s_waitcnt lgkmcnt(0)
	v_mfma_f32_16x16x32_bf16 v[128:131], v[120:123], v[178:181], v[128:131]
	v_mfma_f32_16x16x32_bf16 v[124:127], v[136:139], v[178:181], v[124:127]
	v_mfma_f32_16x16x32_bf16 v[108:111], v[120:123], v[188:191], v[108:111]
	v_mfma_f32_16x16x32_bf16 v[104:107], v[136:139], v[188:191], v[104:107]
	v_mfma_f32_16x16x32_bf16 v[92:95], v[120:123], v[196:199], v[92:95]
	v_mfma_f32_16x16x32_bf16 v[88:91], v[136:139], v[196:199], v[88:91]
	v_mfma_f32_16x16x32_bf16 v[76:79], v[120:123], v[204:207], v[76:79]
	v_mfma_f32_16x16x32_bf16 v[72:75], v[136:139], v[204:207], v[72:75]
	v_mfma_f32_16x16x32_bf16 v[128:131], v[132:135], v[182:185], v[128:131]
	v_mfma_f32_16x16x32_bf16 v[124:127], v[140:143], v[182:185], v[124:127]
	v_mfma_f32_16x16x32_bf16 v[108:111], v[132:135], v[192:195], v[108:111]
	v_mfma_f32_16x16x32_bf16 v[104:107], v[140:143], v[192:195], v[104:107]
	v_mfma_f32_16x16x32_bf16 v[92:95], v[132:135], v[200:203], v[92:95]
	v_mfma_f32_16x16x32_bf16 v[88:91], v[140:143], v[200:203], v[88:91]
	v_mfma_f32_16x16x32_bf16 v[76:79], v[132:135], v[208:211], v[76:79]
	v_mfma_f32_16x16x32_bf16 v[72:75], v[140:143], v[208:211], v[72:75]
	s_setprio 0
	s_setprio 1
	v_mfma_f32_16x16x32_bf16 v[116:119], v[154:157], v[178:181], v[116:119]
	v_mfma_f32_16x16x32_bf16 v[112:115], v[166:169], v[178:181], v[112:115]
	v_mfma_f32_16x16x32_bf16 v[100:103], v[154:157], v[188:191], v[100:103]
	v_mfma_f32_16x16x32_bf16 v[96:99], v[166:169], v[188:191], v[96:99]
	v_mfma_f32_16x16x32_bf16 v[84:87], v[154:157], v[196:199], v[84:87]
	v_mfma_f32_16x16x32_bf16 v[80:83], v[166:169], v[196:199], v[80:83]
	v_mfma_f32_16x16x32_bf16 v[68:71], v[154:157], v[204:207], v[68:71]
	v_mfma_f32_16x16x32_bf16 v[64:67], v[166:169], v[204:207], v[64:67]
	v_mfma_f32_16x16x32_bf16 v[116:119], v[162:165], v[182:185], v[116:119]
	v_mfma_f32_16x16x32_bf16 v[112:115], v[170:173], v[182:185], v[112:115]
	v_mfma_f32_16x16x32_bf16 v[100:103], v[162:165], v[192:195], v[100:103]
	v_mfma_f32_16x16x32_bf16 v[96:99], v[170:173], v[192:195], v[96:99]
	v_mfma_f32_16x16x32_bf16 v[84:87], v[162:165], v[200:203], v[84:87]
	v_mfma_f32_16x16x32_bf16 v[80:83], v[170:173], v[200:203], v[80:83]
	v_mfma_f32_16x16x32_bf16 v[68:71], v[162:165], v[208:211], v[68:71]
	v_mfma_f32_16x16x32_bf16 v[64:67], v[170:173], v[208:211], v[64:67]
	s_setprio 0
	s_barrier
	s_add_i32 s38, s38, s31
	s_add_u32 s90, s24, 0x80
	s_addc_u32 s91, s25, 0
	s_mov_b32 m0, s38
	ds_read_b128 v[178:181], v161 offset:16384
	ds_read_b128 v[182:185], v161 offset:17408
	ds_read_b128 v[188:191], v161 offset:18432
	ds_read_b128 v[192:195], v161 offset:19456
	ds_read_b128 v[196:199], v161 offset:20480
	ds_read_b128 v[200:203], v161 offset:21504
	ds_read_b128 v[204:207], v161 offset:22528
	ds_read_b128 v[208:211], v161 offset:23552
	global_load_lds_dwordx4 v176, s[24:25]
	s_add_i32 m0, s38, 0x2000
	s_add_u32 s80, s24, 0x100000
	s_addc_u32 s81, s25, 0
	s_add_i32 s38, s39, s31
	global_load_lds_dwordx4 v148, s[24:25]
	s_mov_b32 m0, s38
	s_nop 0
	global_load_lds_dwordx4 v176, s[80:81]
	s_add_i32 m0, s38, 0x2000
	s_nop 0
	global_load_lds_dwordx4 v148, s[80:81]
	s_waitcnt vmcnt(6)
	s_waitcnt lgkmcnt(0)
	s_barrier
	s_setprio 1
	s_waitcnt lgkmcnt(0)
	v_mfma_f32_16x16x32_bf16 v[60:63], v[120:123], v[178:181], v[60:63]
	v_mfma_f32_16x16x32_bf16 v[56:59], v[136:139], v[178:181], v[56:59]
	v_mfma_f32_16x16x32_bf16 v[48:51], v[120:123], v[188:191], v[48:51]
	v_mfma_f32_16x16x32_bf16 v[40:43], v[136:139], v[188:191], v[40:43]
	v_mfma_f32_16x16x32_bf16 v[32:35], v[120:123], v[196:199], v[32:35]
	v_mfma_f32_16x16x32_bf16 v[24:27], v[136:139], v[196:199], v[24:27]
	v_mfma_f32_16x16x32_bf16 v[16:19], v[120:123], v[204:207], v[16:19]
	v_mfma_f32_16x16x32_bf16 v[8:11], v[136:139], v[204:207], v[8:11]
	v_mfma_f32_16x16x32_bf16 v[60:63], v[132:135], v[182:185], v[60:63]
	v_mfma_f32_16x16x32_bf16 v[56:59], v[140:143], v[182:185], v[56:59]
	v_mfma_f32_16x16x32_bf16 v[48:51], v[132:135], v[192:195], v[48:51]
	v_mfma_f32_16x16x32_bf16 v[40:43], v[140:143], v[192:195], v[40:43]
	v_mfma_f32_16x16x32_bf16 v[32:35], v[132:135], v[200:203], v[32:35]
	v_mfma_f32_16x16x32_bf16 v[24:27], v[140:143], v[200:203], v[24:27]
	v_mfma_f32_16x16x32_bf16 v[16:19], v[132:135], v[208:211], v[16:19]
	v_mfma_f32_16x16x32_bf16 v[8:11], v[140:143], v[208:211], v[8:11]
	s_setprio 0
	s_setprio 1
	v_mfma_f32_16x16x32_bf16 v[52:55], v[154:157], v[178:181], v[52:55]
	v_mfma_f32_16x16x32_bf16 v[44:47], v[166:169], v[178:181], v[44:47]
	v_mfma_f32_16x16x32_bf16 v[36:39], v[154:157], v[188:191], v[36:39]
	v_mfma_f32_16x16x32_bf16 v[28:31], v[166:169], v[188:191], v[28:31]
	v_mfma_f32_16x16x32_bf16 v[20:23], v[154:157], v[196:199], v[20:23]
	v_mfma_f32_16x16x32_bf16 v[12:15], v[166:169], v[196:199], v[12:15]
	v_mfma_f32_16x16x32_bf16 v[4:7], v[154:157], v[204:207], v[4:7]
	v_mfma_f32_16x16x32_bf16 v[0:3], v[166:169], v[204:207], v[0:3]
	v_mfma_f32_16x16x32_bf16 v[52:55], v[162:165], v[182:185], v[52:55]
	v_mfma_f32_16x16x32_bf16 v[44:47], v[170:173], v[182:185], v[44:47]
	v_mfma_f32_16x16x32_bf16 v[36:39], v[162:165], v[192:195], v[36:39]
	v_mfma_f32_16x16x32_bf16 v[28:31], v[170:173], v[192:195], v[28:31]
	v_mfma_f32_16x16x32_bf16 v[20:23], v[162:165], v[200:203], v[20:23]
	v_mfma_f32_16x16x32_bf16 v[12:15], v[170:173], v[200:203], v[12:15]
	v_mfma_f32_16x16x32_bf16 v[4:7], v[162:165], v[208:211], v[4:7]
	v_mfma_f32_16x16x32_bf16 v[0:3], v[170:173], v[208:211], v[0:3]
	s_setprio 0
	s_barrier
	s_add_i32 s38, 0, 0x18000
	s_add_i32 s39, 0, 0x1c000
	v_add_u32_e32 v140, s38, v160
	v_add_u32_e32 v170, s39, v160
	ds_read_b128 v[120:123], v140
	ds_read_b128 v[132:135], v140 offset:1024
	ds_read_b128 v[136:139], v140 offset:2048
	ds_read_b128 v[140:143], v140 offset:3072
	ds_read_b128 v[154:157], v170
	ds_read_b128 v[162:165], v170 offset:1024
	ds_read_b128 v[166:169], v170 offset:2048
	ds_read_b128 v[170:173], v170 offset:3072
	s_mov_b32 m0, s34
	s_nop 0
	global_load_lds_dwordx4 v144, s[26:27]
	s_mov_b32 m0, s35
	s_nop 0
	global_load_lds_dwordx4 v146, s[26:27]
	s_add_u32 s26, s26, 0x100000
	s_addc_u32 s27, s27, 0
	s_mov_b32 m0, s36
	ds_read_b128 v[178:181], v161 offset:32768
	ds_read_b128 v[182:185], v161 offset:33792
	ds_read_b128 v[188:191], v161 offset:34816
	ds_read_b128 v[192:195], v161 offset:35840
	ds_read_b128 v[196:199], v161 offset:36864
	ds_read_b128 v[200:203], v161 offset:37888
	ds_read_b128 v[204:207], v161 offset:38912
	ds_read_b128 v[208:211], v161 offset:39936
	global_load_lds_dwordx4 v144, s[26:27]
	s_mov_b32 m0, s43
	s_nop 0
	global_load_lds_dwordx4 v146, s[26:27]
	s_waitcnt vmcnt(8)
	s_waitcnt lgkmcnt(0)
	s_barrier
	s_setprio 1
	s_waitcnt lgkmcnt(0)
	v_mfma_f32_16x16x32_bf16 v[128:131], v[120:123], v[178:181], v[128:131]
	v_mfma_f32_16x16x32_bf16 v[124:127], v[136:139], v[178:181], v[124:127]
	v_mfma_f32_16x16x32_bf16 v[108:111], v[120:123], v[188:191], v[108:111]
	v_mfma_f32_16x16x32_bf16 v[104:107], v[136:139], v[188:191], v[104:107]
	v_mfma_f32_16x16x32_bf16 v[92:95], v[120:123], v[196:199], v[92:95]
	v_mfma_f32_16x16x32_bf16 v[88:91], v[136:139], v[196:199], v[88:91]
	v_mfma_f32_16x16x32_bf16 v[76:79], v[120:123], v[204:207], v[76:79]
	v_mfma_f32_16x16x32_bf16 v[72:75], v[136:139], v[204:207], v[72:75]
	v_mfma_f32_16x16x32_bf16 v[128:131], v[132:135], v[182:185], v[128:131]
	v_mfma_f32_16x16x32_bf16 v[124:127], v[140:143], v[182:185], v[124:127]
	v_mfma_f32_16x16x32_bf16 v[108:111], v[132:135], v[192:195], v[108:111]
	v_mfma_f32_16x16x32_bf16 v[104:107], v[140:143], v[192:195], v[104:107]
	v_mfma_f32_16x16x32_bf16 v[92:95], v[132:135], v[200:203], v[92:95]
	v_mfma_f32_16x16x32_bf16 v[88:91], v[140:143], v[200:203], v[88:91]
	v_mfma_f32_16x16x32_bf16 v[76:79], v[132:135], v[208:211], v[76:79]
	v_mfma_f32_16x16x32_bf16 v[72:75], v[140:143], v[208:211], v[72:75]
	s_setprio 0
	s_setprio 1
	v_mfma_f32_16x16x32_bf16 v[116:119], v[154:157], v[178:181], v[116:119]
	v_mfma_f32_16x16x32_bf16 v[112:115], v[166:169], v[178:181], v[112:115]
	v_mfma_f32_16x16x32_bf16 v[100:103], v[154:157], v[188:191], v[100:103]
	v_mfma_f32_16x16x32_bf16 v[96:99], v[166:169], v[188:191], v[96:99]
	v_mfma_f32_16x16x32_bf16 v[84:87], v[154:157], v[196:199], v[84:87]
	v_mfma_f32_16x16x32_bf16 v[80:83], v[166:169], v[196:199], v[80:83]
	v_mfma_f32_16x16x32_bf16 v[68:71], v[154:157], v[204:207], v[68:71]
	v_mfma_f32_16x16x32_bf16 v[64:67], v[166:169], v[204:207], v[64:67]
	v_mfma_f32_16x16x32_bf16 v[116:119], v[162:165], v[182:185], v[116:119]
	v_mfma_f32_16x16x32_bf16 v[112:115], v[170:173], v[182:185], v[112:115]
	v_mfma_f32_16x16x32_bf16 v[100:103], v[162:165], v[192:195], v[100:103]
	v_mfma_f32_16x16x32_bf16 v[96:99], v[170:173], v[192:195], v[96:99]
	v_mfma_f32_16x16x32_bf16 v[84:87], v[162:165], v[200:203], v[84:87]
	v_mfma_f32_16x16x32_bf16 v[80:83], v[170:173], v[200:203], v[80:83]
	v_mfma_f32_16x16x32_bf16 v[68:71], v[162:165], v[208:211], v[68:71]
	v_mfma_f32_16x16x32_bf16 v[64:67], v[170:173], v[208:211], v[64:67]
	s_setprio 0
	s_barrier
	s_add_i32 s26, s38, s31
	s_mov_b32 m0, s26
	ds_read_b128 v[178:181], v161 offset:49152
	ds_read_b128 v[182:185], v161 offset:50176
	ds_read_b128 v[188:191], v161 offset:51200
	ds_read_b128 v[192:195], v161 offset:52224
	ds_read_b128 v[196:199], v161 offset:53248
	ds_read_b128 v[200:203], v161 offset:54272
	ds_read_b128 v[204:207], v161 offset:55296
	ds_read_b128 v[208:211], v161 offset:56320
	global_load_lds_dwordx4 v176, s[90:91]
	s_add_i32 m0, s26, 0x2000
	s_add_u32 s24, s24, 0x100080
	s_addc_u32 s25, s25, 0
	s_add_i32 s26, s39, s31
	global_load_lds_dwordx4 v148, s[90:91]
	s_mov_b32 m0, s26
	s_nop 0
	global_load_lds_dwordx4 v176, s[24:25]
	s_add_i32 m0, s26, 0x2000
	s_nop 0
	global_load_lds_dwordx4 v148, s[24:25]
	s_waitcnt vmcnt(6)
	s_waitcnt lgkmcnt(0)
	s_barrier
	s_setprio 1
	s_waitcnt lgkmcnt(0)
	v_mfma_f32_16x16x32_bf16 v[60:63], v[120:123], v[178:181], v[60:63]
	v_mfma_f32_16x16x32_bf16 v[56:59], v[136:139], v[178:181], v[56:59]
	v_mfma_f32_16x16x32_bf16 v[48:51], v[120:123], v[188:191], v[48:51]
	v_mfma_f32_16x16x32_bf16 v[40:43], v[136:139], v[188:191], v[40:43]
	v_mfma_f32_16x16x32_bf16 v[32:35], v[120:123], v[196:199], v[32:35]
	v_mfma_f32_16x16x32_bf16 v[24:27], v[136:139], v[196:199], v[24:27]
	v_mfma_f32_16x16x32_bf16 v[16:19], v[120:123], v[204:207], v[16:19]
	v_mfma_f32_16x16x32_bf16 v[8:11], v[136:139], v[204:207], v[8:11]
	v_mfma_f32_16x16x32_bf16 v[60:63], v[132:135], v[182:185], v[60:63]
	v_mfma_f32_16x16x32_bf16 v[56:59], v[140:143], v[182:185], v[56:59]
	v_mfma_f32_16x16x32_bf16 v[48:51], v[132:135], v[192:195], v[48:51]
	v_mfma_f32_16x16x32_bf16 v[40:43], v[140:143], v[192:195], v[40:43]
	v_mfma_f32_16x16x32_bf16 v[32:35], v[132:135], v[200:203], v[32:35]
	v_mfma_f32_16x16x32_bf16 v[24:27], v[140:143], v[200:203], v[24:27]
	v_mfma_f32_16x16x32_bf16 v[16:19], v[132:135], v[208:211], v[16:19]
	v_mfma_f32_16x16x32_bf16 v[8:11], v[140:143], v[208:211], v[8:11]
	s_setprio 0
	s_setprio 1
	v_mfma_f32_16x16x32_bf16 v[52:55], v[154:157], v[178:181], v[52:55]
	v_mfma_f32_16x16x32_bf16 v[44:47], v[166:169], v[178:181], v[44:47]
	v_mfma_f32_16x16x32_bf16 v[36:39], v[154:157], v[188:191], v[36:39]
	v_mfma_f32_16x16x32_bf16 v[28:31], v[166:169], v[188:191], v[28:31]
	v_mfma_f32_16x16x32_bf16 v[20:23], v[154:157], v[196:199], v[20:23]
	v_mfma_f32_16x16x32_bf16 v[12:15], v[166:169], v[196:199], v[12:15]
	v_mfma_f32_16x16x32_bf16 v[4:7], v[154:157], v[204:207], v[4:7]
	v_mfma_f32_16x16x32_bf16 v[0:3], v[166:169], v[204:207], v[0:3]
	v_mfma_f32_16x16x32_bf16 v[52:55], v[162:165], v[182:185], v[52:55]
	v_mfma_f32_16x16x32_bf16 v[44:47], v[170:173], v[182:185], v[44:47]
	v_mfma_f32_16x16x32_bf16 v[36:39], v[162:165], v[192:195], v[36:39]
	v_mfma_f32_16x16x32_bf16 v[28:31], v[170:173], v[192:195], v[28:31]
	v_mfma_f32_16x16x32_bf16 v[20:23], v[162:165], v[200:203], v[20:23]
	v_mfma_f32_16x16x32_bf16 v[12:15], v[170:173], v[200:203], v[12:15]
	v_mfma_f32_16x16x32_bf16 v[4:7], v[162:165], v[208:211], v[4:7]
	v_mfma_f32_16x16x32_bf16 v[0:3], v[170:173], v[208:211], v[0:3]
	s_setprio 0
	s_barrier
	s_add_i32 s79, s79, 2
	s_add_u32 s22, s22, 0x100
	s_addc_u32 s23, s23, 0
	s_add_u32 s55, s55, 0x100
	s_addc_u32 s78, s78, 0
	s_cmp_gt_u32 s79, 61
	s_cbranch_scc0 .LBB0_921
	s_and_b64 vcc, exec, s[8:9]
	s_cbranch_vccz .LBB0_924
	s_barrier
